# GEMM K loop: per-segment s_setprio 1/0 flips removed (equal priority for both wave halves)
# speedup vs baseline: 1.0183x; 1.0096x over previous
.LBB0_522:
	s_add_i32 vcc_lo, s74, 2
	s_add_u32 s76, s72, 0x80
	s_addc_u32 s75, s73, 0
	s_add_i32 vcc_hi, 0, 0x10000
	v_add_u32_e32 v140, vcc_hi, v237
	s_waitcnt lgkmcnt(0)
	ds_read_b128 v[128:131], v140
	ds_read_b128 v[132:135], v140 offset:1024
	ds_read_b128 v[136:139], v140 offset:2048
	ds_read_b128 v[140:143], v140 offset:3072
	s_cmp_eq_u32 s50, s74
	s_cselect_b32 s74, s68, s76
	s_cselect_b32 s75, s69, s75
	s_cselect_b32 s77, s71, s79
	s_cselect_b32 s76, s70, s78
	v_lshl_add_u64 v[176:177], s[72:73], 0, v[206:207]
	s_add_i32 m0, s93, 0xc000
	ds_read_b128 v[144:147], v240
	ds_read_b128 v[148:151], v240 offset:1024
	ds_read_b128 v[152:155], v240 offset:2048
	ds_read_b128 v[156:159], v240 offset:3072
	ds_read_b128 v[160:163], v240 offset:4096
	ds_read_b128 v[164:167], v240 offset:5120
	ds_read_b128 v[168:171], v240 offset:6144
	ds_read_b128 v[172:175], v240 offset:7168
	global_load_lds_dwordx4 v[176:177], off
	v_lshl_add_u64 v[176:177], s[72:73], 0, v[208:209]
	s_add_i32 m0, s93, 0xe000
	s_nop 0
	global_load_lds_dwordx4 v[176:177], off
	s_waitcnt lgkmcnt(8)
	s_barrier
	s_waitcnt lgkmcnt(0)
	s_waitcnt lgkmcnt(0)
	v_mfma_f32_16x16x32_bf16 v[124:127], v[128:131], v[144:147], v[124:127]
	v_mfma_f32_16x16x32_bf16 v[120:123], v[136:139], v[144:147], v[120:123]
	v_mfma_f32_16x16x32_bf16 v[116:119], v[128:131], v[152:155], v[116:119]
	v_mfma_f32_16x16x32_bf16 v[112:115], v[136:139], v[152:155], v[112:115]
	v_mfma_f32_16x16x32_bf16 v[100:103], v[128:131], v[160:163], v[100:103]
	v_mfma_f32_16x16x32_bf16 v[96:99], v[136:139], v[160:163], v[96:99]
	v_mfma_f32_16x16x32_bf16 v[84:87], v[128:131], v[168:171], v[84:87]
	v_mfma_f32_16x16x32_bf16 v[80:83], v[136:139], v[168:171], v[80:83]
	v_mfma_f32_16x16x32_bf16 v[124:127], v[132:135], v[148:151], v[124:127]
	v_mfma_f32_16x16x32_bf16 v[120:123], v[140:143], v[148:151], v[120:123]
	v_mfma_f32_16x16x32_bf16 v[116:119], v[132:135], v[156:159], v[116:119]
	v_mfma_f32_16x16x32_bf16 v[112:115], v[140:143], v[156:159], v[112:115]
	v_mfma_f32_16x16x32_bf16 v[100:103], v[132:135], v[164:167], v[100:103]
	v_mfma_f32_16x16x32_bf16 v[96:99], v[140:143], v[164:167], v[96:99]
	v_mfma_f32_16x16x32_bf16 v[84:87], v[132:135], v[172:175], v[84:87]
	v_mfma_f32_16x16x32_bf16 v[80:83], v[140:143], v[172:175], v[80:83]
	s_barrier
	s_add_i32 s31, 0, 0x14000
	s_add_i32 vcc_hi, vcc_hi, s87
	v_add_u32_e32 v188, s31, v237
	v_lshl_add_u64 v[210:211], s[76:77], 0, v[196:197]
	s_mov_b32 m0, vcc_hi
	ds_read_b128 v[176:179], v188
	ds_read_b128 v[180:183], v188 offset:1024
	ds_read_b128 v[184:187], v188 offset:2048
	ds_read_b128 v[188:191], v188 offset:3072
	global_load_lds_dwordx4 v[210:211], off
	v_lshl_add_u64 v[212:213], s[76:77], 0, v[200:201]
	s_add_i32 m0, vcc_hi, 0x2000
	s_nop 0
	global_load_lds_dwordx4 v[212:213], off
	s_barrier
	s_waitcnt lgkmcnt(0)
	s_waitcnt lgkmcnt(0)
	v_mfma_f32_16x16x32_bf16 v[108:111], v[176:179], v[144:147], v[108:111]
	v_mfma_f32_16x16x32_bf16 v[104:107], v[184:187], v[144:147], v[104:107]
	v_mfma_f32_16x16x32_bf16 v[92:95], v[176:179], v[152:155], v[92:95]
	v_mfma_f32_16x16x32_bf16 v[88:91], v[184:187], v[152:155], v[88:91]
	v_mfma_f32_16x16x32_bf16 v[76:79], v[176:179], v[160:163], v[76:79]
	v_mfma_f32_16x16x32_bf16 v[72:75], v[184:187], v[160:163], v[72:75]
	v_mfma_f32_16x16x32_bf16 v[68:71], v[176:179], v[168:171], v[68:71]
	v_mfma_f32_16x16x32_bf16 v[64:67], v[184:187], v[168:171], v[64:67]
	v_mfma_f32_16x16x32_bf16 v[108:111], v[180:183], v[148:151], v[108:111]
	v_mfma_f32_16x16x32_bf16 v[104:107], v[188:191], v[148:151], v[104:107]
	v_mfma_f32_16x16x32_bf16 v[92:95], v[180:183], v[156:159], v[92:95]
	v_mfma_f32_16x16x32_bf16 v[88:91], v[188:191], v[156:159], v[88:91]
	v_mfma_f32_16x16x32_bf16 v[76:79], v[180:183], v[164:167], v[76:79]
	v_mfma_f32_16x16x32_bf16 v[72:75], v[188:191], v[164:167], v[72:75]
	v_mfma_f32_16x16x32_bf16 v[68:71], v[180:183], v[172:175], v[68:71]
	v_mfma_f32_16x16x32_bf16 v[64:67], v[188:191], v[172:175], v[64:67]
	s_mov_b32 m0, s93
	v_lshl_add_u64 v[214:215], s[74:75], 0, v[194:195]
	s_barrier
	ds_read_b128 v[144:147], v240 offset:16384
	ds_read_b128 v[148:151], v240 offset:17408
	ds_read_b128 v[152:155], v240 offset:18432
	ds_read_b128 v[156:159], v240 offset:19456
	ds_read_b128 v[160:163], v240 offset:20480
	ds_read_b128 v[164:167], v240 offset:21504
	ds_read_b128 v[168:171], v240 offset:22528
	ds_read_b128 v[172:175], v240 offset:23552
	global_load_lds_dwordx4 v[214:215], off
	v_lshl_add_u64 v[216:217], s[74:75], 0, v[198:199]
	s_mov_b32 m0, s54
	s_nop 0
	global_load_lds_dwordx4 v[216:217], off
	s_barrier
	s_waitcnt lgkmcnt(0)
	s_waitcnt lgkmcnt(0)
	v_mfma_f32_16x16x32_bf16 v[60:63], v[128:131], v[144:147], v[60:63]
	v_mfma_f32_16x16x32_bf16 v[56:59], v[136:139], v[144:147], v[56:59]
	v_mfma_f32_16x16x32_bf16 v[52:55], v[128:131], v[152:155], v[52:55]
	v_mfma_f32_16x16x32_bf16 v[48:51], v[136:139], v[152:155], v[48:51]
	v_mfma_f32_16x16x32_bf16 v[36:39], v[128:131], v[160:163], v[36:39]
	v_mfma_f32_16x16x32_bf16 v[32:35], v[136:139], v[160:163], v[32:35]
	v_mfma_f32_16x16x32_bf16 v[20:23], v[128:131], v[168:171], v[20:23]
	v_mfma_f32_16x16x32_bf16 v[16:19], v[136:139], v[168:171], v[16:19]
	v_mfma_f32_16x16x32_bf16 v[60:63], v[132:135], v[148:151], v[60:63]
	v_mfma_f32_16x16x32_bf16 v[56:59], v[140:143], v[148:151], v[56:59]
	v_mfma_f32_16x16x32_bf16 v[52:55], v[132:135], v[156:159], v[52:55]
	v_mfma_f32_16x16x32_bf16 v[48:51], v[140:143], v[156:159], v[48:51]
	v_mfma_f32_16x16x32_bf16 v[36:39], v[132:135], v[164:167], v[36:39]
	v_mfma_f32_16x16x32_bf16 v[32:35], v[140:143], v[164:167], v[32:35]
	v_mfma_f32_16x16x32_bf16 v[20:23], v[132:135], v[172:175], v[20:23]
	v_mfma_f32_16x16x32_bf16 v[16:19], v[140:143], v[172:175], v[16:19]
	s_barrier
	s_add_u32 s76, s76, s20
	s_addc_u32 s77, s77, 0
	s_add_i32 s31, s31, s87
	v_lshl_add_u64 v[218:219], s[76:77], 0, v[196:197]
	s_mov_b32 m0, s31
	v_lshl_add_u64 v[220:221], s[76:77], 0, v[200:201]
	global_load_lds_dwordx4 v[218:219], off
	s_add_i32 m0, s31, 0x2000
	s_nop 0
	global_load_lds_dwordx4 v[220:221], off
	s_waitcnt vmcnt(6)
	s_barrier
	v_mfma_f32_16x16x32_bf16 v[44:47], v[176:179], v[144:147], v[44:47]
	v_mfma_f32_16x16x32_bf16 v[40:43], v[184:187], v[144:147], v[40:43]
	v_mfma_f32_16x16x32_bf16 v[28:31], v[176:179], v[152:155], v[28:31]
	v_mfma_f32_16x16x32_bf16 v[24:27], v[184:187], v[152:155], v[24:27]
	v_mfma_f32_16x16x32_bf16 v[12:15], v[176:179], v[160:163], v[12:15]
	v_mfma_f32_16x16x32_bf16 v[8:11], v[184:187], v[160:163], v[8:11]
	v_mfma_f32_16x16x32_bf16 v[4:7], v[176:179], v[168:171], v[4:7]
	v_mfma_f32_16x16x32_bf16 v[0:3], v[184:187], v[168:171], v[0:3]
	v_mfma_f32_16x16x32_bf16 v[44:47], v[180:183], v[148:151], v[44:47]
	v_mfma_f32_16x16x32_bf16 v[40:43], v[188:191], v[148:151], v[40:43]
	v_mfma_f32_16x16x32_bf16 v[28:31], v[180:183], v[156:159], v[28:31]
	v_mfma_f32_16x16x32_bf16 v[24:27], v[188:191], v[156:159], v[24:27]
	v_mfma_f32_16x16x32_bf16 v[12:15], v[180:183], v[164:167], v[12:15]
	v_mfma_f32_16x16x32_bf16 v[8:11], v[188:191], v[164:167], v[8:11]
	v_mfma_f32_16x16x32_bf16 v[4:7], v[180:183], v[172:175], v[4:7]
	v_mfma_f32_16x16x32_bf16 v[0:3], v[188:191], v[172:175], v[0:3]
	s_add_i32 s31, 0, 0x18000
	v_add_u32_e32 v140, s31, v237
	s_barrier
	ds_read_b128 v[128:131], v140
	ds_read_b128 v[132:135], v140 offset:1024
	ds_read_b128 v[136:139], v140 offset:2048
	ds_read_b128 v[140:143], v140 offset:3072
	s_add_u32 s74, s74, s20
	s_addc_u32 s75, s75, 0
	s_mov_b32 m0, s34
	v_lshl_add_u64 v[176:177], s[74:75], 0, v[194:195]
	ds_read_b128 v[144:147], v240 offset:32768
	ds_read_b128 v[148:151], v240 offset:33792
	ds_read_b128 v[152:155], v240 offset:34816
	ds_read_b128 v[156:159], v240 offset:35840
	ds_read_b128 v[160:163], v240 offset:36864
	ds_read_b128 v[164:167], v240 offset:37888
	ds_read_b128 v[168:171], v240 offset:38912
	ds_read_b128 v[172:175], v240 offset:39936
	global_load_lds_dwordx4 v[176:177], off
	v_lshl_add_u64 v[176:177], s[74:75], 0, v[198:199]
	s_mov_b32 m0, s35
	s_nop 0
	global_load_lds_dwordx4 v[176:177], off
	s_waitcnt lgkmcnt(8)
	s_barrier
	s_waitcnt lgkmcnt(0)
	s_waitcnt lgkmcnt(0)
	v_mfma_f32_16x16x32_bf16 v[124:127], v[128:131], v[144:147], v[124:127]
	v_mfma_f32_16x16x32_bf16 v[120:123], v[136:139], v[144:147], v[120:123]
	v_mfma_f32_16x16x32_bf16 v[116:119], v[128:131], v[152:155], v[116:119]
	v_mfma_f32_16x16x32_bf16 v[112:115], v[136:139], v[152:155], v[112:115]
	v_mfma_f32_16x16x32_bf16 v[100:103], v[128:131], v[160:163], v[100:103]
	v_mfma_f32_16x16x32_bf16 v[96:99], v[136:139], v[160:163], v[96:99]
	v_mfma_f32_16x16x32_bf16 v[84:87], v[128:131], v[168:171], v[84:87]
	v_mfma_f32_16x16x32_bf16 v[80:83], v[136:139], v[168:171], v[80:83]
	v_mfma_f32_16x16x32_bf16 v[124:127], v[132:135], v[148:151], v[124:127]
	v_mfma_f32_16x16x32_bf16 v[120:123], v[140:143], v[148:151], v[120:123]
	v_mfma_f32_16x16x32_bf16 v[116:119], v[132:135], v[156:159], v[116:119]
	v_mfma_f32_16x16x32_bf16 v[112:115], v[140:143], v[156:159], v[112:115]
	v_mfma_f32_16x16x32_bf16 v[100:103], v[132:135], v[164:167], v[100:103]
	v_mfma_f32_16x16x32_bf16 v[96:99], v[140:143], v[164:167], v[96:99]
	v_mfma_f32_16x16x32_bf16 v[84:87], v[132:135], v[172:175], v[84:87]
	v_mfma_f32_16x16x32_bf16 v[80:83], v[140:143], v[172:175], v[80:83]
	s_barrier
	s_add_i32 s74, 0, 0x1c000
	s_add_i32 s31, s31, s87
	v_add_u32_e32 v188, s74, v237
	v_lshl_add_u64 v[210:211], v[210:211], 0, s[60:61]
	s_mov_b32 m0, s31
	ds_read_b128 v[176:179], v188
	ds_read_b128 v[180:183], v188 offset:1024
	ds_read_b128 v[184:187], v188 offset:2048
	ds_read_b128 v[188:191], v188 offset:3072
	global_load_lds_dwordx4 v[210:211], off
	v_lshl_add_u64 v[210:211], v[212:213], 0, s[60:61]
	s_add_i32 m0, s31, 0x2000
	s_nop 0
	global_load_lds_dwordx4 v[210:211], off
	s_barrier
	s_waitcnt lgkmcnt(0)
	s_waitcnt lgkmcnt(0)
	v_mfma_f32_16x16x32_bf16 v[108:111], v[176:179], v[144:147], v[108:111]
	v_mfma_f32_16x16x32_bf16 v[104:107], v[184:187], v[144:147], v[104:107]
	v_mfma_f32_16x16x32_bf16 v[92:95], v[176:179], v[152:155], v[92:95]
	v_mfma_f32_16x16x32_bf16 v[88:91], v[184:187], v[152:155], v[88:91]
	v_mfma_f32_16x16x32_bf16 v[76:79], v[176:179], v[160:163], v[76:79]
	v_mfma_f32_16x16x32_bf16 v[72:75], v[184:187], v[160:163], v[72:75]
	v_mfma_f32_16x16x32_bf16 v[68:71], v[176:179], v[168:171], v[68:71]
	v_mfma_f32_16x16x32_bf16 v[64:67], v[184:187], v[168:171], v[64:67]
	v_mfma_f32_16x16x32_bf16 v[108:111], v[180:183], v[148:151], v[108:111]
	v_mfma_f32_16x16x32_bf16 v[104:107], v[188:191], v[148:151], v[104:107]
	v_mfma_f32_16x16x32_bf16 v[92:95], v[180:183], v[156:159], v[92:95]
	v_mfma_f32_16x16x32_bf16 v[88:91], v[188:191], v[156:159], v[88:91]
	v_mfma_f32_16x16x32_bf16 v[76:79], v[180:183], v[164:167], v[76:79]
	v_mfma_f32_16x16x32_bf16 v[72:75], v[188:191], v[164:167], v[72:75]
	v_mfma_f32_16x16x32_bf16 v[68:71], v[180:183], v[172:175], v[68:71]
	v_mfma_f32_16x16x32_bf16 v[64:67], v[188:191], v[172:175], v[64:67]
	s_mov_b32 m0, s97
	v_lshl_add_u64 v[210:211], v[214:215], 0, s[60:61]
	s_barrier
	ds_read_b128 v[144:147], v240 offset:49152
	ds_read_b128 v[148:151], v240 offset:50176
	ds_read_b128 v[152:155], v240 offset:51200
	ds_read_b128 v[156:159], v240 offset:52224
	ds_read_b128 v[160:163], v240 offset:53248
	ds_read_b128 v[164:167], v240 offset:54272
	ds_read_b128 v[168:171], v240 offset:55296
	ds_read_b128 v[172:175], v240 offset:56320
	global_load_lds_dwordx4 v[210:211], off
	v_lshl_add_u64 v[210:211], v[216:217], 0, s[60:61]
	s_mov_b32 m0, s36
	s_nop 0
	global_load_lds_dwordx4 v[210:211], off
	s_barrier
	s_waitcnt lgkmcnt(0)
	s_waitcnt lgkmcnt(0)
	v_mfma_f32_16x16x32_bf16 v[60:63], v[128:131], v[144:147], v[60:63]
	v_mfma_f32_16x16x32_bf16 v[56:59], v[136:139], v[144:147], v[56:59]
	v_mfma_f32_16x16x32_bf16 v[52:55], v[128:131], v[152:155], v[52:55]
	v_mfma_f32_16x16x32_bf16 v[48:51], v[136:139], v[152:155], v[48:51]
	v_mfma_f32_16x16x32_bf16 v[36:39], v[128:131], v[160:163], v[36:39]
	v_mfma_f32_16x16x32_bf16 v[32:35], v[136:139], v[160:163], v[32:35]
	v_mfma_f32_16x16x32_bf16 v[20:23], v[128:131], v[168:171], v[20:23]
	v_mfma_f32_16x16x32_bf16 v[16:19], v[136:139], v[168:171], v[16:19]
	v_mfma_f32_16x16x32_bf16 v[60:63], v[132:135], v[148:151], v[60:63]
	v_mfma_f32_16x16x32_bf16 v[56:59], v[140:143], v[148:151], v[56:59]
	v_mfma_f32_16x16x32_bf16 v[52:55], v[132:135], v[156:159], v[52:55]
	v_mfma_f32_16x16x32_bf16 v[48:51], v[140:143], v[156:159], v[48:51]
	v_mfma_f32_16x16x32_bf16 v[36:39], v[132:135], v[164:167], v[36:39]
	v_mfma_f32_16x16x32_bf16 v[32:35], v[140:143], v[164:167], v[32:35]
	v_mfma_f32_16x16x32_bf16 v[20:23], v[132:135], v[172:175], v[20:23]
	v_mfma_f32_16x16x32_bf16 v[16:19], v[140:143], v[172:175], v[16:19]
	s_barrier
	s_add_i32 s31, s74, s87
	v_lshl_add_u64 v[128:129], v[218:219], 0, s[60:61]
	s_mov_b32 m0, s31
	s_nop 0
	global_load_lds_dwordx4 v[128:129], off
	v_lshl_add_u64 v[128:129], v[220:221], 0, s[60:61]
	s_add_i32 m0, s31, 0x2000
	s_nop 0
	global_load_lds_dwordx4 v[128:129], off
	s_waitcnt vmcnt(6)
	s_barrier
	v_mfma_f32_16x16x32_bf16 v[44:47], v[176:179], v[144:147], v[44:47]
	v_mfma_f32_16x16x32_bf16 v[40:43], v[184:187], v[144:147], v[40:43]
	v_mfma_f32_16x16x32_bf16 v[28:31], v[176:179], v[152:155], v[28:31]
	v_mfma_f32_16x16x32_bf16 v[24:27], v[184:187], v[152:155], v[24:27]
	v_mfma_f32_16x16x32_bf16 v[12:15], v[176:179], v[160:163], v[12:15]
	v_mfma_f32_16x16x32_bf16 v[8:11], v[184:187], v[160:163], v[8:11]
	v_mfma_f32_16x16x32_bf16 v[4:7], v[176:179], v[168:171], v[4:7]
	v_mfma_f32_16x16x32_bf16 v[0:3], v[184:187], v[168:171], v[0:3]
	v_mfma_f32_16x16x32_bf16 v[44:47], v[180:183], v[148:151], v[44:47]
	v_mfma_f32_16x16x32_bf16 v[40:43], v[188:191], v[148:151], v[40:43]
	v_mfma_f32_16x16x32_bf16 v[28:31], v[180:183], v[156:159], v[28:31]
	v_mfma_f32_16x16x32_bf16 v[24:27], v[188:191], v[156:159], v[24:27]
	v_mfma_f32_16x16x32_bf16 v[12:15], v[180:183], v[164:167], v[12:15]
	v_mfma_f32_16x16x32_bf16 v[8:11], v[188:191], v[164:167], v[8:11]
	v_mfma_f32_16x16x32_bf16 v[4:7], v[180:183], v[172:175], v[4:7]
	v_mfma_f32_16x16x32_bf16 v[0:3], v[188:191], v[172:175], v[0:3]
	s_add_u32 s72, s72, 0x100
	s_addc_u32 s73, s73, 0
	s_add_u32 s78, s78, 0x100
	s_addc_u32 s79, s79, 0
	s_cmp_ge_u32 vcc_lo, s30
	s_mov_b32 s74, vcc_lo
	s_barrier
	s_cbranch_scc0 .LBB0_522
	s_cmp_lt_i32 s91, 0
	s_mov_b64 s[72:73], -1
	s_cbranch_scc0 .LBB0_716
	s_lshl_b32 s78, s46, 8
	s_cmp_lt_i32 s81, 2
	s_cbranch_scc1 .LBB0_582
	s_cmp_lt_i32 s81, 3
	s_cbranch_scc1 .LBB0_579
	s_cmp_lg_u32 s81, 3
	s_cbranch_scc0 .LBB0_544
	v_lshl_or_b32 v128, s19, 7, v238
	v_ashrrev_i32_e32 v129, 31, v128
	v_lshl_add_u64 v[144:145], v[128:129], 1, s[24:25]
	v_and_b32_e32 v129, 64, v231
	v_xor_b32_e32 v128, 16, v231
	v_add_u32_e32 v129, 64, v129
	v_cmp_lt_i32_e32 vcc, v128, v129
	v_add_u32_e32 v146, s78, v202
	v_ashrrev_i32_e32 v147, 31, v146
	v_cndmask_b32_e32 v128, v231, v128, vcc
	v_lshlrev_b32_e32 v167, 2, v128
	v_xor_b32_e32 v128, 32, v231
	v_cmp_lt_i32_e32 vcc, v128, v129
	v_or_b32_e32 v156, 16, v146
	v_ashrrev_i32_e32 v157, 31, v156
	v_cndmask_b32_e32 v128, v231, v128, vcc
	v_lshlrev_b32_e32 v166, 2, v128
	v_lshlrev_b64 v[128:129], 12, v[146:147]
	v_lshl_add_u64 v[160:161], v[144:145], 0, v[128:129]
	global_load_dwordx4 v[140:143], v[160:161], off
	v_or_b32_e32 v152, 32, v146
	v_lshlrev_b64 v[128:129], 12, v[156:157]
	v_ashrrev_i32_e32 v153, 31, v152
	v_or_b32_e32 v148, 48, v146
	v_lshl_add_u64 v[158:159], v[144:145], 0, v[128:129]
	v_lshlrev_b64 v[128:129], 12, v[152:153]
	v_ashrrev_i32_e32 v149, 31, v148
	v_lshl_add_u64 v[154:155], v[144:145], 0, v[128:129]
	v_lshlrev_b64 v[128:129], 12, v[148:149]
	v_lshl_add_u64 v[150:151], v[144:145], 0, v[128:129]
	global_load_dwordx4 v[136:139], v[158:159], off
	global_load_dwordx4 v[132:135], v[154:155], off
	global_load_dwordx4 v[128:131], v[150:151], off
	v_mul_f32_e32 v163, 0xbfb8aa3b, v104
	v_exp_f32_e32 v163, v163
	v_mul_f32_e32 v162, 0xbfb8aa3b, v108
	v_exp_f32_e32 v162, v162
	v_add_f32_e32 v163, 1.0, v163
	v_rcp_f32_e32 v164, v163
	v_mul_f32_e32 v163, 0xbfb8aa3b, v109
	v_exp_f32_e32 v163, v163
	v_add_f32_e32 v162, 1.0, v162
	v_rcp_f32_e32 v162, v162
	v_add_f32_e32 v163, 1.0, v163
	v_rcp_f32_e32 v163, v163
	s_waitcnt vmcnt(0)
	v_lshlrev_b32_e32 v168, 16, v140
	v_and_b32_e32 v169, 0xffff0000, v140
	v_mul_f32_e32 v140, 0xbfb8aa3b, v105
	v_exp_f32_e32 v140, v140
	v_pk_fma_f32 v[162:163], v[162:163], v[124:125], v[168:169]
	v_lshlrev_b32_e32 v168, 16, v142
	v_and_b32_e32 v169, 0xffff0000, v142
	v_add_f32_e32 v140, 1.0, v140
	v_rcp_f32_e32 v165, v140
	v_mul_f32_e32 v140, 0xbfb8aa3b, v110
	v_exp_f32_e32 v140, v140
	v_mul_f32_e32 v142, 0xbfb8aa3b, v111
	v_pk_fma_f32 v[164:165], v[164:165], v[120:121], v[168:169]
	v_lshlrev_b32_e32 v170, 16, v141
	v_add_f32_e32 v140, 1.0, v140
	v_rcp_f32_e32 v168, v140
	v_mul_f32_e32 v140, 0xbfb8aa3b, v106
	v_and_b32_e32 v171, 0xffff0000, v141
	v_mul_f32_e32 v141, 0xbfb8aa3b, v107
	v_exp_f32_e32 v140, v140
	v_exp_f32_e32 v142, v142
	v_exp_f32_e32 v141, v141
	v_add_f32_e32 v140, 1.0, v140
	v_add_f32_e32 v142, 1.0, v142
	v_add_f32_e32 v141, 1.0, v141
	v_rcp_f32_e32 v140, v140
	v_rcp_f32_e32 v169, v142
	v_rcp_f32_e32 v141, v141
	v_lshlrev_b32_e32 v142, 16, v143
	v_and_b32_e32 v143, 0xffff0000, v143
	v_pk_fma_f32 v[168:169], v[168:169], v[126:127], v[170:171]
	v_pk_fma_f32 v[170:171], v[140:141], v[122:123], v[142:143]
	v_cvt_pk_bf16_f32 v140, v162, v163
	v_cvt_pk_bf16_f32 v141, v168, v169
	v_cvt_pk_bf16_f32 v142, v164, v165
	v_cvt_pk_bf16_f32 v143, v170, v171
	global_store_dwordx4 v[160:161], v[140:143], off
	v_pk_mul_f32 v[160:161], v[164:165], v[164:165]
	s_nop 0
	v_pk_mul_f32 v[140:141], v[162:163], v[162:163]
	v_pk_mul_f32 v[142:143], v[168:169], v[168:169]
	v_add_f32_e32 v140, v140, v141
	v_add_f32_e32 v142, v142, v143
	v_pk_mul_f32 v[162:163], v[170:171], v[170:171]
	v_add_f32_e32 v140, v140, v142
	v_add_f32_e32 v141, v160, v161
	v_add_f32_e32 v162, v162, v163
	v_add_f32_e32 v140, v141, v140
	v_add_f32_e32 v140, v162, v140
	ds_bpermute_b32 v141, v167, v140
	s_waitcnt lgkmcnt(0)
	v_add_f32_e32 v140, v140, v141
	ds_bpermute_b32 v141, v166, v140
	s_and_saveexec_b64 s[72:73], s[6:7]
	s_cbranch_execz .LBB0_529
	s_waitcnt lgkmcnt(0)
	v_add_f32_e32 v142, v140, v141
	s_lshl_b32 s74, s19, 2
	v_lshlrev_b64 v[140:141], 8, v[146:147]
	s_ashr_i32 s75, s74, 31
	v_lshl_add_u64 v[140:141], s[26:27], 0, v[140:141]
	v_lshl_add_u64 v[140:141], s[74:75], 2, v[140:141]
	s_lshl_b32 s50, s37, 2
	v_lshl_add_u64 v[140:141], v[140:141], 0, s[50:51]
	global_store_dword v[140:141], v142, off
